# s10 + attention: partialSM max/alpha/fma/exp(p0) hoisted from the barrier-to-barrier VALU segment into the P.V MFMA segment (in-place exp + movs)
# baseline (speedup 1.0000x reference)
; #define SBAR() __builtin_amdgcn_sched_barrier(0)
; #define SLOAD(i, k0) do { sr_[i].vs0 = St::ld8(&Vh[(long)((k0) + sr) * LDK + sc]); sr_[i].vs1 = St::ld8(&Vh[(long)((k0) + 32 + sr) * LDK + sc]); \
;     sr_[i].ks0 = St::ld8(&Kh[(long)((k0) + sr) * LDK + sc]); sr_[i].ks1 = St::ld8(&Kh[(long)((k0) + 32 + sr) * LDK + sc]); } while (0)
; __device__ __forceinline__ void finishSM(f32x16& p0, f32x16& p1, float alpha, float& l_reg, bf16x8& pa0, bf16x8& pa1, bf16x8& pa2, bf16x8& pa3) {
;   for (int r = 0; r < 16; ++r) p1[r] = __builtin_amdgcn_exp2f(p1[r]);
;   float ps = 0; for (int r = 0; r < 16; ++r) ps += p0[r]; for (int r = 0; r < 16; ++r) ps += p1[r];
;   { auto rr = __builtin_amdgcn_permlane32_swap(__float_as_uint(ps), __float_as_uint(ps), false, false);
;     ps = __uint_as_float(rr[0]) + __uint_as_float(rr[1]); }
;   l_reg = l_reg * alpha + ps;
;     ...
;   PK4(p0, 0, pa0); PK4(p0, 8, pa1); PK4(p1, 0, pa2); PK4(p1, 8, pa3);
;     ...
; }
; __device__ __forceinline__ void qkt(f32x16& p0, f32x16& p1, const bf16* Ks, const bf16x8* qr, int r32, int hi) {
;   p0 = f32x16{}; p1 = f32x16{};
;   for (int d0 = 0; d0 < 8; ++d0) { int cb = (d0 * 16 + hi * 8) * 2;
;     bf16x8 b0 = *reinterpret_cast<const bf16x8*>((const char*)Ks + KSWZ(r32, cb));
;     bf16x8 b1 = *reinterpret_cast<const bf16x8*>((const char*)Ks + KSWZ(32 + r32, cb));
;     p0 = __builtin_amdgcn_mfma_f32_32x32x16_bf16(b0, qr[d0], p0, 0, 0, 0);
;     p1 = __builtin_amdgcn_mfma_f32_32x32x16_bf16(b1, qr[d0], p1, 0, 0, 0); }
; }
; __device__ __forceinline__ void attn_dense_body(const bf16* __restrict__ Qb, const bf16* __restrict__ Kh, const bf16* __restrict__ Vh,
;                                                 const unsigned short* __restrict__ Gb, unsigned short* __restrict__ Yb, int seq, char* lds, const int tid) {
;     ...
;     SBAR(); qkt(pB0, pB1, (bf16*)((char*)K_lds + SHM_K), qr, r32, hi);
;     finishSM(pA0, pA1, alA, l_reg, pa0, pa1, pa2, pa3); SBAR();
;     SLOAD(SO, (j + SDEPTH) * KVBLK); SBAR();
.LBB0_602:
	ds_read_b128 v[64:67], v192 offset:49152
	ds_read_b128 v[68:71], v192 offset:57344
	ds_read_b128 v[146:149], v201 offset:49152
	ds_read_b128 v[150:153], v201 offset:57344
	v_exp_f32_e32 v160, v162
	v_add_f32_e32 v162, 0, v223
	s_waitcnt lgkmcnt(3)
	v_mfma_f32_32x32x16_bf16 v[80:95], v[64:67], v[126:129], 0
	v_add_f32_e32 v162, v224, v162
	v_add_f32_e32 v162, v225, v162
	v_add_f32_e32 v162, v227, v162
	v_add_f32_e32 v162, v229, v162
	v_add_f32_e32 v162, v230, v162
	v_add_f32_e32 v162, v226, v162
	v_add_f32_e32 v162, v228, v162
	s_waitcnt lgkmcnt(2)
	v_mfma_f32_32x32x16_bf16 v[64:79], v[68:71], v[126:129], 0
	v_add_f32_e32 v162, v215, v162
	v_add_f32_e32 v162, v217, v162
	v_add_f32_e32 v162, v219, v162
	v_add_f32_e32 v162, v221, v162
	v_add_f32_e32 v162, v216, v162
	v_add_f32_e32 v162, v218, v162
	v_add_f32_e32 v162, v220, v162
	s_waitcnt lgkmcnt(1)
	v_mfma_f32_32x32x16_bf16 v[80:95], v[146:149], v[122:125], v[80:95]
	v_add_f32_e32 v162, v222, v162
	v_exp_f32_e32 v154, v164
	v_exp_f32_e32 v155, v165
	v_exp_f32_e32 v156, v172
	v_exp_f32_e32 v157, v173
	v_exp_f32_e32 v158, v168
	v_exp_f32_e32 v159, v169
	s_waitcnt lgkmcnt(0)
	v_mfma_f32_32x32x16_bf16 v[64:79], v[150:153], v[122:125], v[64:79]
	ds_read_b128 v[146:149], v200 offset:49152
	ds_read_b128 v[150:153], v200 offset:57344
	v_exp_f32_e32 v161, v163
	v_cvt_pk_bf16_f32 v164, v229, v230
	v_cvt_pk_bf16_f32 v163, v225, v227
	v_cvt_pk_bf16_f32 v165, v226, v228
	v_cvt_pk_bf16_f32 v168, v216, v218
	v_cvt_pk_bf16_f32 v169, v220, v222
	s_waitcnt lgkmcnt(1)
	v_mfma_f32_32x32x16_bf16 v[80:95], v[146:149], v[134:137], v[80:95]
	v_permlane32_swap_b32_e32 v163, v165
	s_waitcnt lgkmcnt(0)
	v_mfma_f32_32x32x16_bf16 v[64:79], v[150:153], v[134:137], v[64:79]
	ds_read_b128 v[146:149], v195 offset:49152
	ds_read_b128 v[150:153], v195 offset:57344
	s_waitcnt lgkmcnt(1)
	v_mfma_f32_32x32x16_bf16 v[80:95], v[146:149], v[130:133], v[80:95]
	s_waitcnt lgkmcnt(0)
	v_mfma_f32_32x32x16_bf16 v[64:79], v[150:153], v[130:133], v[64:79]
	ds_read_b128 v[146:149], v194 offset:49152
	ds_read_b128 v[150:153], v194 offset:57344
	s_waitcnt lgkmcnt(1)
	v_mfma_f32_32x32x16_bf16 v[80:95], v[146:149], v[118:121], v[80:95]
	s_waitcnt lgkmcnt(0)
	v_mfma_f32_32x32x16_bf16 v[64:79], v[150:153], v[118:121], v[64:79]
	ds_read_b128 v[146:149], v193 offset:49152
	ds_read_b128 v[150:153], v193 offset:57344
	s_waitcnt lgkmcnt(1)
	v_mfma_f32_32x32x16_bf16 v[80:95], v[146:149], v[114:117], v[80:95]
	s_waitcnt lgkmcnt(0)
	v_mfma_f32_32x32x16_bf16 v[64:79], v[150:153], v[114:117], v[64:79]
	ds_read_b128 v[146:149], v207 offset:49152
	ds_read_b128 v[150:153], v207 offset:57344
	s_waitcnt lgkmcnt(1)
	v_mfma_f32_32x32x16_bf16 v[80:95], v[146:149], v[110:113], v[80:95]
	s_waitcnt lgkmcnt(0)
	v_mfma_f32_32x32x16_bf16 v[64:79], v[150:153], v[110:113], v[64:79]
	ds_read_b128 v[146:149], v206 offset:49152
	ds_read_b128 v[150:153], v206 offset:57344
	s_waitcnt lgkmcnt(1)
	v_mfma_f32_32x32x16_bf16 v[80:95], v[146:149], v[106:109], v[80:95]
	v_exp_f32_e32 v146, v176
	v_exp_f32_e32 v147, v177
	v_exp_f32_e32 v148, v174
	v_exp_f32_e32 v149, v175
	v_add_f32_e32 v162, v146, v162
	v_add_f32_e32 v162, v147, v162
	v_add_f32_e32 v162, v148, v162
	s_waitcnt lgkmcnt(0)
	v_mfma_f32_32x32x16_bf16 v[64:79], v[150:153], v[106:109], v[64:79]
	v_exp_f32_e32 v150, v170
	v_exp_f32_e32 v151, v171
	v_exp_f32_e32 v152, v166
	v_exp_f32_e32 v153, v167
	v_add_f32_e32 v162, v149, v162
	v_add_f32_e32 v162, v150, v162
	v_add_f32_e32 v162, v151, v162
	v_add_f32_e32 v162, v152, v162
	v_add_f32_e32 v162, v153, v162
	v_add_f32_e32 v162, v154, v162
	v_add_f32_e32 v162, v155, v162
	v_add_f32_e32 v162, v156, v162
	v_add_f32_e32 v162, v157, v162
	v_add_f32_e32 v162, v158, v162
	v_add_f32_e32 v162, v159, v162
	v_add_f32_e32 v162, v160, v162
	v_add_f32_e32 v211, v161, v162
	v_mov_b32_e32 v212, v211
	v_cvt_pk_bf16_f32 v162, v223, v224
	s_nop 0
	v_permlane32_swap_b32_e32 v211, v212
	v_permlane32_swap_b32_e32 v162, v164
	v_cvt_pk_bf16_f32 v166, v215, v217
	v_cvt_pk_bf16_f32 v167, v219, v221
	v_cvt_pk_bf16_f32 v170, v146, v147
	v_cvt_pk_bf16_f32 v171, v148, v149
	v_cvt_pk_bf16_f32 v172, v150, v151
	v_cvt_pk_bf16_f32 v173, v152, v153
	v_cvt_pk_bf16_f32 v174, v154, v155
	v_cvt_pk_bf16_f32 v175, v156, v157
	v_cvt_pk_bf16_f32 v176, v158, v159
	v_cvt_pk_bf16_f32 v177, v160, v161
	v_permlane32_swap_b32_e32 v166, v168
	v_permlane32_swap_b32_e32 v167, v169
	v_permlane32_swap_b32_e32 v170, v172
	v_permlane32_swap_b32_e32 v171, v173
	v_permlane32_swap_b32_e32 v174, v176
	v_permlane32_swap_b32_e32 v175, v177
	v_add_co_u32_e32 v146, vcc, s69, v182
	s_mov_b32 s8, 0xffff0000
	s_nop 0
	v_addc_co_u32_e32 v147, vcc, -1, v183, vcc
	v_add_co_u32_e32 v150, vcc, s8, v182
	s_mov_b32 s8, 0xff6e8000
	s_nop 0
	v_addc_co_u32_e32 v151, vcc, -1, v183, vcc
	v_add_co_u32_e32 v154, vcc, s8, v182
	s_mov_b32 s8, 0xff6f0000
	s_nop 0
	v_addc_co_u32_e32 v155, vcc, -1, v183, vcc
	v_add_co_u32_e32 v158, vcc, s8, v182
	global_load_dwordx4 v[146:149], v[146:147], off
	s_nop 0
	global_load_dwordx4 v[150:153], v[150:151], off
	v_addc_co_u32_e32 v159, vcc, -1, v183, vcc
	global_load_dwordx4 v[154:157], v[154:155], off
	s_nop 0
	global_load_dwordx4 v[158:161], v[158:159], off
	ds_read_b64_tr_b16 v[214:215], v179 offset:0
	ds_read_b64_tr_b16 v[216:217], v179 offset:0x800
	ds_read_b64_tr_b16 v[218:219], v179 offset:0x1000
	ds_read_b64_tr_b16 v[220:221], v179 offset:0x1800
	ds_read_b64_tr_b16 v[222:223], v179 offset:0x2000
	ds_read_b64_tr_b16 v[224:225], v179 offset:0x2800
	ds_read_b64_tr_b16 v[226:227], v179 offset:0x3000
	ds_read_b64_tr_b16 v[228:229], v179 offset:0x3800
	s_waitcnt lgkmcnt(0)
; #define SBAR() __builtin_amdgcn_sched_barrier(0)
; __device__ __forceinline__ void partialSM(f32x16& p0, f32x16& p1, float& m_reg, float& mn, float& alpha) {
;   constexpr float C = SCALE * 1.4426950408889634f;
;   float pmax = p0[0]; for (int r = 1; r < 16; ++r) pmax = fmaxf(pmax, p0[r]); for (int r = 0; r < 16; ++r) pmax = fmaxf(pmax, p1[r]);
;   { auto rr = __builtin_amdgcn_permlane32_swap(__float_as_uint(pmax), __float_as_uint(pmax), false, false);
;     pmax = fmaxf(__uint_as_float(rr[0]), __uint_as_float(rr[1])); }
;   if (__builtin_expect(__all(pmax - m_reg <= THR / SCALE), 1)) { mn = m_reg; alpha = 1.f; }
;   else { mn = fmaxf(m_reg, pmax); alpha = __builtin_amdgcn_exp2f((m_reg - mn) * C); m_reg = mn; }
;   float mnC = -mn * C;
;   for (int r = 0; r < 16; ++r) p0[r] = fmaf(p0[r], C, mnC); for (int r = 0; r < 16; ++r) p1[r] = fmaf(p1[r], C, mnC);
;   for (int r = 0; r < 16; ++r) p0[r] = __builtin_amdgcn_exp2f(p0[r]);
; }
; template <int D0> __device__ __forceinline__ void pv_one(f32x16& od, int vb, bf16x8 pa0, bf16x8 pa1, bf16x8 pa2, bf16x8 pa3) {
;   const s16x4 l0 = tr_read<v_rd_off(D0, 0, 0)>(vb), h0 = tr_read<v_rd_off(D0, 0, 1)>(vb), l1 = tr_read<v_rd_off(D0, 1, 0)>(vb), h1 = tr_read<v_rd_off(D0, 1, 1)>(vb);
;   const s16x4 l2 = tr_read<v_rd_off(D0, 2, 0)>(vb), h2 = tr_read<v_rd_off(D0, 2, 1)>(vb), l3 = tr_read<v_rd_off(D0, 3, 0)>(vb), h3 = tr_read<v_rd_off(D0, 3, 1)>(vb);
;   asm volatile("s_waitcnt lgkmcnt(0)" ::: "memory"); SBAR();
;     ...
;   od = __builtin_amdgcn_mfma_f32_32x32x16_bf16(pa0, PK(l0, h0), od, 0, 0, 0);
;   od = __builtin_amdgcn_mfma_f32_32x32x16_bf16(pa1, PK(l1, h1), od, 0, 0, 0);
;   od = __builtin_amdgcn_mfma_f32_32x32x16_bf16(pa2, PK(l2, h2), od, 0, 0, 0);
;   od = __builtin_amdgcn_mfma_f32_32x32x16_bf16(pa3, PK(l3, h3), od, 0, 0, 0);
;     ...
; }
; __device__ __forceinline__ void pv_d0(f32x16* o, int vb, bf16x8 pa0, bf16x8 pa1, bf16x8 pa2, bf16x8 pa3) {
;   pv_one<0>(o[0], vb, pa0, pa1, pa2, pa3); pv_one<1>(o[1], vb, pa0, pa1, pa2, pa3); pv_one<2>(o[2], vb, pa0, pa1, pa2, pa3); pv_one<3>(o[3], vb, pa0, pa1, pa2, pa3);
	s_nop 0
	v_mfma_f32_32x32x16_bf16 v[0:15], v[162:165], v[214:217], v[0:15]
	ds_read_b64_tr_b16 v[214:215], v179 offset:0x200
	ds_read_b64_tr_b16 v[216:217], v179 offset:0xa00
	v_max_f32_e32 v232, v81, v81
	v_max_f32_e32 v233, v80, v80
	v_max_f32_e32 v232, v233, v232
	v_max3_f32 v232, v232, v82, v83
	v_max3_f32 v232, v232, v84, v85
	v_max3_f32 v232, v232, v86, v87
	v_mfma_f32_32x32x16_bf16 v[0:15], v[166:169], v[218:221], v[0:15]
	ds_read_b64_tr_b16 v[218:219], v179 offset:0x1200
	ds_read_b64_tr_b16 v[220:221], v179 offset:0x1a00
	v_max3_f32 v232, v232, v88, v89
	v_max3_f32 v232, v232, v90, v91
	v_max3_f32 v232, v232, v92, v93
	v_max3_f32 v232, v232, v94, v95
	v_max3_f32 v232, v232, v64, v65
	v_max3_f32 v232, v232, v66, v67
	v_mfma_f32_32x32x16_bf16 v[0:15], v[170:173], v[222:225], v[0:15]
	ds_read_b64_tr_b16 v[222:223], v179 offset:0x2200
	ds_read_b64_tr_b16 v[224:225], v179 offset:0x2a00
	v_max3_f32 v232, v232, v68, v69
	v_max3_f32 v232, v232, v70, v71
	v_max3_f32 v232, v232, v72, v73
	v_max3_f32 v232, v232, v74, v75
	v_max3_f32 v232, v232, v76, v77
	v_max3_f32 v232, v232, v78, v79
	v_mfma_f32_32x32x16_bf16 v[0:15], v[174:177], v[226:229], v[0:15]
	ds_read_b64_tr_b16 v[226:227], v179 offset:0x3200
	ds_read_b64_tr_b16 v[228:229], v179 offset:0x3a00
	v_mov_b32_e32 v233, v232
	s_nop 1
	v_permlane32_swap_b32_e32 v232, v233
	v_max_f32_e32 v233, v233, v233
	v_max_f32_e32 v232, v232, v232
	v_max_f32_e32 v232, v232, v233
	s_waitcnt lgkmcnt(0)
	v_mfma_f32_32x32x16_bf16 v[48:63], v[162:165], v[214:217], v[48:63]
	ds_read_b64_tr_b16 v[214:215], v179 offset:0x400
	ds_read_b64_tr_b16 v[216:217], v179 offset:0xc00
	v_sub_f32_e32 v233, v232, v210
	v_cmp_ge_f32_e32 vcc, s68, v233
	v_max_f32_e32 v233, v210, v210
	v_max_f32_e32 v232, v233, v232
	v_sub_f32_e32 v233, v210, v232
	v_mul_f32_e32 v233, 0x3e0293ee, v233
	v_mfma_f32_32x32x16_bf16 v[48:63], v[166:169], v[218:221], v[48:63]
	ds_read_b64_tr_b16 v[218:219], v179 offset:0x1400
	ds_read_b64_tr_b16 v[220:221], v179 offset:0x1c00
	s_cmp_eq_u64 vcc, exec
	s_cselect_b64 s[8:9], -1, 0
	v_exp_f32_e32 v233, v233
	v_mfma_f32_32x32x16_bf16 v[48:63], v[170:173], v[222:225], v[48:63]
	ds_read_b64_tr_b16 v[222:223], v179 offset:0x2400
	ds_read_b64_tr_b16 v[224:225], v179 offset:0x2c00
	v_cndmask_b32_e64 v210, v232, v210, s[8:9]
	v_mul_f32_e32 v213, 0xbe0293ee, v210
	v_fmamk_f32 v80, v80, 0x3e0293ee, v213
	v_fmamk_f32 v81, v81, 0x3e0293ee, v213
	v_fmamk_f32 v82, v82, 0x3e0293ee, v213
	v_fmamk_f32 v83, v83, 0x3e0293ee, v213
	v_mfma_f32_32x32x16_bf16 v[48:63], v[174:177], v[226:229], v[48:63]
	ds_read_b64_tr_b16 v[226:227], v179 offset:0x3400
	ds_read_b64_tr_b16 v[228:229], v179 offset:0x3c00
	v_fmamk_f32 v84, v84, 0x3e0293ee, v213
	v_fmamk_f32 v85, v85, 0x3e0293ee, v213
	v_fmamk_f32 v86, v86, 0x3e0293ee, v213
	v_fmamk_f32 v87, v87, 0x3e0293ee, v213
	v_fmamk_f32 v88, v88, 0x3e0293ee, v213
	v_fmamk_f32 v89, v89, 0x3e0293ee, v213
	s_waitcnt lgkmcnt(0)
	v_mfma_f32_32x32x16_bf16 v[32:47], v[162:165], v[214:217], v[32:47]
	ds_read_b64_tr_b16 v[214:215], v179 offset:0x600
	ds_read_b64_tr_b16 v[216:217], v179 offset:0xe00
	v_fmamk_f32 v90, v90, 0x3e0293ee, v213
	v_fmamk_f32 v91, v91, 0x3e0293ee, v213
	v_fmamk_f32 v92, v92, 0x3e0293ee, v213
	v_fmamk_f32 v93, v93, 0x3e0293ee, v213
	v_fmamk_f32 v94, v94, 0x3e0293ee, v213
	v_fmamk_f32 v95, v95, 0x3e0293ee, v213
	v_mfma_f32_32x32x16_bf16 v[32:47], v[166:169], v[218:221], v[32:47]
	ds_read_b64_tr_b16 v[218:219], v179 offset:0x1600
	ds_read_b64_tr_b16 v[220:221], v179 offset:0x1e00
	v_exp_f32_e32 v80, v80
	v_exp_f32_e32 v81, v81
	v_exp_f32_e32 v82, v82
	v_mfma_f32_32x32x16_bf16 v[32:47], v[170:173], v[222:225], v[32:47]
	ds_read_b64_tr_b16 v[222:223], v179 offset:0x2600
	ds_read_b64_tr_b16 v[224:225], v179 offset:0x2e00
	v_exp_f32_e32 v83, v83
	v_exp_f32_e32 v84, v84
	v_exp_f32_e32 v85, v85
	v_mfma_f32_32x32x16_bf16 v[32:47], v[174:177], v[226:229], v[32:47]
	ds_read_b64_tr_b16 v[226:227], v179 offset:0x3600
	ds_read_b64_tr_b16 v[228:229], v179 offset:0x3e00
	v_exp_f32_e32 v86, v86
	v_exp_f32_e32 v87, v87
	v_exp_f32_e32 v88, v88
	s_waitcnt lgkmcnt(0)
	v_mfma_f32_32x32x16_bf16 v[16:31], v[162:165], v[214:217], v[16:31]
	v_exp_f32_e32 v89, v89
	v_exp_f32_e32 v90, v90
	v_exp_f32_e32 v91, v91
	v_mfma_f32_32x32x16_bf16 v[16:31], v[166:169], v[218:221], v[16:31]
	v_exp_f32_e32 v92, v92
	v_exp_f32_e32 v93, v93
	v_mfma_f32_32x32x16_bf16 v[16:31], v[170:173], v[222:225], v[16:31]
	v_exp_f32_e32 v94, v94
	v_exp_f32_e32 v95, v95
	v_mfma_f32_32x32x16_bf16 v[16:31], v[174:177], v[226:229], v[16:31]
	s_barrier
	s_waitcnt vmcnt(4)
	v_cndmask_b32_e64 v214, v233, 1.0, s[8:9]
	v_cmp_gt_f32_e32 vcc, 1.0, v214
	s_waitcnt vmcnt(7)
	ds_write_b128 v204, v[98:101]
	s_waitcnt vmcnt(6)
	ds_write_b128 v205, v[138:141]
	s_waitcnt vmcnt(5)
	ds_write_b128 v202, v[102:105] offset:32768
	s_waitcnt vmcnt(4)
	ds_write_b128 v203, v[142:145] offset:32768
	s_cbranch_vccz .LBB0_606
	s_and_saveexec_b64 s[12:13], s[6:7]
	ds_write_b32 v189, v214 offset:128
	s_or_b64 exec, exec, s[12:13]
	s_waitcnt lgkmcnt(0)
	v_add_u32_e32 v163, v181, v180
	ds_read_b128 v[164:167], v163 offset:224
	ds_read_b128 v[168:171], v163 offset:192
	ds_read_b128 v[172:175], v163 offset:160
	ds_read_b128 v[216:219], v163 offset:128
	s_waitcnt lgkmcnt(3)
	v_pk_mul_f32 v[12:13], v[12:13], v[164:165]
	s_waitcnt lgkmcnt(2)
	v_pk_mul_f32 v[8:9], v[8:9], v[168:169]
	s_waitcnt lgkmcnt(1)
	v_pk_mul_f32 v[4:5], v[4:5], v[172:173]
	v_pk_mul_f32 v[14:15], v[14:15], v[166:167]
	v_pk_mul_f32 v[10:11], v[10:11], v[170:171]
	v_pk_mul_f32 v[6:7], v[6:7], v[174:175]
	s_waitcnt lgkmcnt(0)
	v_pk_mul_f32 v[2:3], v[2:3], v[218:219]
	v_pk_mul_f32 v[0:1], v[0:1], v[216:217]
	v_pk_mul_f32 v[60:61], v[60:61], v[164:165]
	v_pk_mul_f32 v[56:57], v[56:57], v[168:169]
	v_pk_mul_f32 v[52:53], v[52:53], v[172:173]
	v_pk_mul_f32 v[62:63], v[62:63], v[166:167]
	v_pk_mul_f32 v[58:59], v[58:59], v[170:171]
	v_pk_mul_f32 v[54:55], v[54:55], v[174:175]
	v_pk_mul_f32 v[50:51], v[50:51], v[218:219]
	v_pk_mul_f32 v[48:49], v[48:49], v[216:217]
	v_pk_mul_f32 v[44:45], v[44:45], v[164:165]
	v_pk_mul_f32 v[40:41], v[40:41], v[168:169]
	v_pk_mul_f32 v[36:37], v[36:37], v[172:173]
	v_pk_mul_f32 v[46:47], v[46:47], v[166:167]
	v_pk_mul_f32 v[42:43], v[42:43], v[170:171]
	v_pk_mul_f32 v[38:39], v[38:39], v[174:175]
	v_pk_mul_f32 v[34:35], v[34:35], v[218:219]
	v_pk_mul_f32 v[32:33], v[32:33], v[216:217]
	v_pk_mul_f32 v[28:29], v[28:29], v[164:165]
	v_pk_mul_f32 v[24:25], v[24:25], v[168:169]
	v_pk_mul_f32 v[20:21], v[20:21], v[172:173]
	v_pk_mul_f32 v[30:31], v[30:31], v[166:167]
	v_pk_mul_f32 v[26:27], v[26:27], v[170:171]
	v_pk_mul_f32 v[22:23], v[22:23], v[174:175]
	v_pk_mul_f32 v[18:19], v[18:19], v[218:219]
	v_pk_mul_f32 v[16:17], v[16:17], v[216:217]
; #define SBAR() __builtin_amdgcn_sched_barrier(0)
; #define SLOAD(i, k0) do { sr_[i].vs0 = St::ld8(&Vh[(long)((k0) + sr) * LDK + sc]); sr_[i].vs1 = St::ld8(&Vh[(long)((k0) + 32 + sr) * LDK + sc]); \
;     sr_[i].ks0 = St::ld8(&Kh[(long)((k0) + sr) * LDK + sc]); sr_[i].ks1 = St::ld8(&Kh[(long)((k0) + 32 + sr) * LDK + sc]); } while (0)
; #define SWAIT() do { if constexpr (SDEPTH == 2) asm volatile("s_waitcnt vmcnt(4)" ::: "memory"); else asm volatile("s_waitcnt vmcnt(0)" ::: "memory"); } while (0)
; #define RESC(a) do { if (__any((a) < 1.f)) { if (hi == 0) al_l[r32] = (a); asm volatile("s_waitcnt lgkmcnt(0)" ::: "memory"); \
;     for (int d = 0; d < 4; ++d) for (int r = 0; r < 16; ++r) o[d][r] *= al_l[crow(r, hi)]; } } while (0)
; __device__ __forceinline__ void partialSM(f32x16& p0, f32x16& p1, float& m_reg, float& mn, float& alpha) {
;     ...
;   for (int r = 0; r < 16; ++r) p0[r] = fmaf(p0[r], C, mnC); for (int r = 0; r < 16; ++r) p1[r] = fmaf(p1[r], C, mnC);
;   for (int r = 0; r < 16; ++r) p0[r] = __builtin_amdgcn_exp2f(p0[r]);
; }
; __device__ __forceinline__ void finishSM(f32x16& p0, f32x16& p1, float alpha, float& l_reg, bf16x8& pa0, bf16x8& pa1, bf16x8& pa2, bf16x8& pa3) {
;   for (int r = 0; r < 16; ++r) p1[r] = __builtin_amdgcn_exp2f(p1[r]);
;   float ps = 0; for (int r = 0; r < 16; ++r) ps += p0[r]; for (int r = 0; r < 16; ++r) ps += p1[r];
;   { auto rr = __builtin_amdgcn_permlane32_swap(__float_as_uint(ps), __float_as_uint(ps), false, false);
;     ps = __uint_as_float(rr[0]) + __uint_as_float(rr[1]); }
;   l_reg = l_reg * alpha + ps;
;     ...
;   PK4(p0, 0, pa0); PK4(p0, 8, pa1); PK4(p1, 0, pa2); PK4(p1, 8, pa3);
;     ...
; }
; __device__ __forceinline__ void attn_dense_body(const bf16* __restrict__ Qb, const bf16* __restrict__ Kh, const bf16* __restrict__ Vh,
;                                                 const unsigned short* __restrict__ Gb, unsigned short* __restrict__ Yb, int seq, char* lds, const int tid) {
;     ...
;     __syncthreads(); SWAIT(); SWRITE(0, SE);
;     RESC(alB); __syncthreads();
;     SBAR(); qkt(pA0, pA1, K_lds, qr, r32, hi);
;     finishSM(pB0, pB1, alB, l_reg, pa0, pa1, pa2, pa3); SBAR();
;     if (SDEPTH == 1 || j + 3 < NT) SLOAD(SE, (j + 1 + SDEPTH) * KVBLK); SBAR();
.LBB0_606:
	v_mov_b32_e32 v162, v80
	v_mov_b32_e32 v163, v81
	v_mov_b32_e32 v164, v82
	v_mov_b32_e32 v175, v83
	v_mov_b32_e32 v176, v84
	v_mov_b32_e32 v177, v85
	v_mov_b32_e32 v165, v86
	v_mov_b32_e32 v174, v87
	v_mov_b32_e32 v166, v88
	v_mov_b32_e32 v167, v89
	v_mov_b32_e32 v172, v90
	v_mov_b32_e32 v173, v91
	v_mov_b32_e32 v168, v92
	v_mov_b32_e32 v169, v93
	v_mov_b32_e32 v170, v94
	v_mov_b32_e32 v171, v95
	v_fmamk_f32 v223, v64, 0x3e0293ee, v213
	v_fmamk_f32 v224, v65, 0x3e0293ee, v213
	v_fmamk_f32 v225, v66, 0x3e0293ee, v213
	v_fmamk_f32 v226, v67, 0x3e0293ee, v213
	v_fmamk_f32 v227, v68, 0x3e0293ee, v213
	v_fmamk_f32 v216, v69, 0x3e0293ee, v213
	v_fmamk_f32 v217, v70, 0x3e0293ee, v213
	v_fmamk_f32 v218, v71, 0x3e0293ee, v213
	v_fmamk_f32 v219, v72, 0x3e0293ee, v213
	v_fmamk_f32 v220, v73, 0x3e0293ee, v213
	v_fmamk_f32 v221, v74, 0x3e0293ee, v213
	v_fmamk_f32 v222, v75, 0x3e0293ee, v213
	v_fmamk_f32 v215, v76, 0x3e0293ee, v213
	v_fmamk_f32 v228, v77, 0x3e0293ee, v213
	v_fmamk_f32 v229, v78, 0x3e0293ee, v213
	v_fmac_f32_e32 v213, 0x3e0293ee, v79
	s_waitcnt lgkmcnt(0)
	s_barrier
	ds_read_b128 v[64:67], v192 offset:32768
	ds_read_b128 v[68:71], v192 offset:40960
	ds_read_b128 v[242:245], v201 offset:32768
	ds_read_b128 v[246:249], v201 offset:40960
	v_add_f32_e32 v230, 0, v162
	v_add_f32_e32 v230, v163, v230
	s_waitcnt lgkmcnt(3)
	v_mfma_f32_32x32x16_bf16 v[80:95], v[64:67], v[126:129], 0
	v_add_f32_e32 v230, v164, v230
	v_add_f32_e32 v230, v175, v230
	v_add_f32_e32 v230, v176, v230
	v_add_f32_e32 v230, v177, v230
	v_add_f32_e32 v230, v165, v230
	v_add_f32_e32 v230, v174, v230
	v_add_f32_e32 v230, v166, v230
	s_waitcnt lgkmcnt(2)
	v_mfma_f32_32x32x16_bf16 v[64:79], v[68:71], v[126:129], 0
	v_add_f32_e32 v230, v167, v230
	v_add_f32_e32 v230, v172, v230
	v_add_f32_e32 v230, v173, v230
	v_exp_f32_e32 v223, v223
	v_add_f32_e32 v230, v168, v230
	v_exp_f32_e32 v224, v224
	v_add_f32_e32 v230, v169, v230
	s_waitcnt lgkmcnt(1)
	v_mfma_f32_32x32x16_bf16 v[80:95], v[242:245], v[122:125], v[80:95]
	v_exp_f32_e32 v225, v225
	v_add_f32_e32 v230, v170, v230
	v_exp_f32_e32 v226, v226
	v_add_f32_e32 v230, v171, v230
	v_exp_f32_e32 v227, v227
	v_add_f32_e32 v230, v223, v230
	v_exp_f32_e32 v216, v216
	s_waitcnt lgkmcnt(0)
	v_mfma_f32_32x32x16_bf16 v[64:79], v[246:249], v[122:125], v[64:79]
	ds_read_b128 v[242:245], v200 offset:32768
	ds_read_b128 v[246:249], v200 offset:40960
	v_add_f32_e32 v230, v224, v230
	v_exp_f32_e32 v217, v217
	v_add_f32_e32 v230, v225, v230
	v_exp_f32_e32 v218, v218
	v_add_f32_e32 v230, v226, v230
	v_exp_f32_e32 v219, v219
	s_waitcnt lgkmcnt(1)
	v_mfma_f32_32x32x16_bf16 v[80:95], v[242:245], v[134:137], v[80:95]
	v_add_f32_e32 v230, v227, v230
	v_exp_f32_e32 v220, v220
	v_add_f32_e32 v230, v216, v230
	v_exp_f32_e32 v221, v221
	v_add_f32_e32 v230, v217, v230
	v_exp_f32_e32 v222, v222
	v_add_f32_e32 v230, v218, v230
	s_waitcnt lgkmcnt(0)
	v_mfma_f32_32x32x16_bf16 v[64:79], v[246:249], v[134:137], v[64:79]
	ds_read_b128 v[242:245], v195 offset:32768
	ds_read_b128 v[246:249], v195 offset:40960
	v_exp_f32_e32 v215, v215
	v_add_f32_e32 v230, v219, v230
	v_exp_f32_e32 v228, v228
	v_add_f32_e32 v230, v220, v230
	v_exp_f32_e32 v229, v229
	v_add_f32_e32 v230, v221, v230
	s_waitcnt lgkmcnt(1)
	v_mfma_f32_32x32x16_bf16 v[80:95], v[242:245], v[130:133], v[80:95]
	v_exp_f32_e32 v213, v213
	v_add_f32_e32 v230, v222, v230
	v_add_f32_e32 v230, v215, v230
	v_add_f32_e32 v230, v228, v230
	v_add_f32_e32 v230, v229, v230
	v_add_f32_e32 v231, v213, v230
	v_mov_b32_e32 v241, v231
	s_waitcnt lgkmcnt(0)
	v_mfma_f32_32x32x16_bf16 v[64:79], v[246:249], v[130:133], v[64:79]
	ds_read_b128 v[242:245], v194 offset:32768
	ds_read_b128 v[246:249], v194 offset:40960
	v_cvt_pk_bf16_f32 v162, v162, v163
	v_cvt_pk_bf16_f32 v163, v164, v175
	v_cvt_pk_bf16_f32 v164, v176, v177
	v_cvt_pk_bf16_f32 v165, v165, v174
	v_cvt_pk_bf16_f32 v166, v166, v167
	v_cvt_pk_bf16_f32 v167, v172, v173
	s_waitcnt lgkmcnt(1)
	v_mfma_f32_32x32x16_bf16 v[80:95], v[242:245], v[118:121], v[80:95]
	v_cvt_pk_bf16_f32 v168, v168, v169
	v_cvt_pk_bf16_f32 v169, v170, v171
	v_cvt_pk_bf16_f32 v170, v223, v224
	v_cvt_pk_bf16_f32 v171, v225, v226
	v_cvt_pk_bf16_f32 v172, v227, v216
	v_cvt_pk_bf16_f32 v173, v217, v218
	v_cvt_pk_bf16_f32 v174, v219, v220
	s_waitcnt lgkmcnt(0)
	v_mfma_f32_32x32x16_bf16 v[64:79], v[246:249], v[118:121], v[64:79]
	ds_read_b128 v[242:245], v193 offset:32768
	ds_read_b128 v[246:249], v193 offset:40960
	v_cvt_pk_bf16_f32 v175, v221, v222
	v_cvt_pk_bf16_f32 v176, v215, v228
	v_cvt_pk_bf16_f32 v177, v229, v213
	v_permlane32_swap_b32_e32 v231, v241
	v_permlane32_swap_b32_e32 v162, v164
	s_waitcnt lgkmcnt(1)
	v_mfma_f32_32x32x16_bf16 v[80:95], v[242:245], v[114:117], v[80:95]
	v_permlane32_swap_b32_e32 v163, v165
	v_permlane32_swap_b32_e32 v166, v168
	v_permlane32_swap_b32_e32 v167, v169
	v_permlane32_swap_b32_e32 v170, v172
	s_waitcnt lgkmcnt(0)
	v_mfma_f32_32x32x16_bf16 v[64:79], v[246:249], v[114:117], v[64:79]
	ds_read_b128 v[242:245], v207 offset:32768
	ds_read_b128 v[246:249], v207 offset:40960
	v_permlane32_swap_b32_e32 v171, v173
	v_permlane32_swap_b32_e32 v174, v176
	v_permlane32_swap_b32_e32 v175, v177
	s_waitcnt lgkmcnt(1)
	v_mfma_f32_32x32x16_bf16 v[80:95], v[242:245], v[110:113], v[80:95]
	s_waitcnt lgkmcnt(0)
	v_mfma_f32_32x32x16_bf16 v[64:79], v[246:249], v[110:113], v[64:79]
	ds_read_b128 v[242:245], v206 offset:32768
	ds_read_b128 v[246:249], v206 offset:40960
	s_waitcnt lgkmcnt(1)
	v_mfma_f32_32x32x16_bf16 v[80:95], v[242:245], v[106:109], v[80:95]
	s_waitcnt lgkmcnt(0)
	v_mfma_f32_32x32x16_bf16 v[64:79], v[246:249], v[106:109], v[64:79]
	s_cmp_ge_u32 s40, s41
	s_cselect_b64 s[12:13], -1, 0
	s_and_b64 vcc, exec, s[12:13]
	s_cbranch_vccnz .LBB0_608
	v_add_co_u32_e32 v98, vcc, 0xffff8000, v182
	s_nop 1
	v_addc_co_u32_e32 v99, vcc, -1, v183, vcc
	v_add_co_u32_e32 v102, vcc, 0xff6f8000, v182
	s_nop 1
	v_addc_co_u32_e32 v103, vcc, -1, v183, vcc
	v_add_co_u32_e32 v142, vcc, 0xff700000, v182
	global_load_dwordx4 v[98:101], v[98:99], off
	s_nop 0
	global_load_dwordx4 v[102:105], v[102:103], off
	v_addc_co_u32_e32 v143, vcc, -1, v183, vcc
	global_load_dwordx4 v[138:141], v[182:183], off
	s_nop 0
	global_load_dwordx4 v[142:145], v[142:143], off
; #define SBAR() __builtin_amdgcn_sched_barrier(0)
; __device__ __forceinline__ void partialSM(f32x16& p0, f32x16& p1, float& m_reg, float& mn, float& alpha) {
;   constexpr float C = SCALE * 1.4426950408889634f;
;   float pmax = p0[0]; for (int r = 1; r < 16; ++r) pmax = fmaxf(pmax, p0[r]); for (int r = 0; r < 16; ++r) pmax = fmaxf(pmax, p1[r]);
;   { auto rr = __builtin_amdgcn_permlane32_swap(__float_as_uint(pmax), __float_as_uint(pmax), false, false);
;     pmax = fmaxf(__uint_as_float(rr[0]), __uint_as_float(rr[1])); }
;   if (__builtin_expect(__all(pmax - m_reg <= THR / SCALE), 1)) { mn = m_reg; alpha = 1.f; }
;   else { mn = fmaxf(m_reg, pmax); alpha = __builtin_amdgcn_exp2f((m_reg - mn) * C); m_reg = mn; }
;   float mnC = -mn * C;
;   for (int r = 0; r < 16; ++r) p0[r] = fmaf(p0[r], C, mnC); for (int r = 0; r < 16; ++r) p1[r] = fmaf(p1[r], C, mnC);
;   for (int r = 0; r < 16; ++r) p0[r] = __builtin_amdgcn_exp2f(p0[r]);
; }
; template <int D0> __device__ __forceinline__ void pv_one(f32x16& od, int vb, bf16x8 pa0, bf16x8 pa1, bf16x8 pa2, bf16x8 pa3) {
;   const s16x4 l0 = tr_read<v_rd_off(D0, 0, 0)>(vb), h0 = tr_read<v_rd_off(D0, 0, 1)>(vb), l1 = tr_read<v_rd_off(D0, 1, 0)>(vb), h1 = tr_read<v_rd_off(D0, 1, 1)>(vb);
;   const s16x4 l2 = tr_read<v_rd_off(D0, 2, 0)>(vb), h2 = tr_read<v_rd_off(D0, 2, 1)>(vb), l3 = tr_read<v_rd_off(D0, 3, 0)>(vb), h3 = tr_read<v_rd_off(D0, 3, 1)>(vb);
;   asm volatile("s_waitcnt lgkmcnt(0)" ::: "memory"); SBAR();
;     ...
;   od = __builtin_amdgcn_mfma_f32_32x32x16_bf16(pa0, PK(l0, h0), od, 0, 0, 0);
;   od = __builtin_amdgcn_mfma_f32_32x32x16_bf16(pa1, PK(l1, h1), od, 0, 0, 0);
;   od = __builtin_amdgcn_mfma_f32_32x32x16_bf16(pa2, PK(l2, h2), od, 0, 0, 0);
;   od = __builtin_amdgcn_mfma_f32_32x32x16_bf16(pa3, PK(l3, h3), od, 0, 0, 0);
;     ...
; }
; __device__ __forceinline__ void pv_d0(f32x16* o, int vb, bf16x8 pa0, bf16x8 pa1, bf16x8 pa2, bf16x8 pa3) {
;   pv_one<0>(o[0], vb, pa0, pa1, pa2, pa3); pv_one<1>(o[1], vb, pa0, pa1, pa2, pa3); pv_one<2>(o[2], vb, pa0, pa1, pa2, pa3); pv_one<3>(o[3], vb, pa0, pa1, pa2, pa3);
.LBB0_608:
	ds_read_b64_tr_b16 v[216:217], v191 offset:0
	ds_read_b64_tr_b16 v[218:219], v191 offset:0x800
	ds_read_b64_tr_b16 v[220:221], v191 offset:0x1000
	ds_read_b64_tr_b16 v[222:223], v191 offset:0x1800
	ds_read_b64_tr_b16 v[224:225], v191 offset:0x2000
	ds_read_b64_tr_b16 v[226:227], v191 offset:0x2800
	ds_read_b64_tr_b16 v[242:243], v191 offset:0x3000
	ds_read_b64_tr_b16 v[244:245], v191 offset:0x3800
	s_waitcnt lgkmcnt(0)
	s_nop 0
	v_mfma_f32_32x32x16_bf16 v[0:15], v[162:165], v[216:219], v[0:15]
	ds_read_b64_tr_b16 v[216:217], v191 offset:0x200
	ds_read_b64_tr_b16 v[218:219], v191 offset:0xa00
	v_max_f32_e32 v232, v81, v81
	v_max_f32_e32 v233, v80, v80
	v_max_f32_e32 v232, v233, v232
	v_max3_f32 v232, v232, v82, v83
	v_max3_f32 v232, v232, v84, v85
	v_max3_f32 v232, v232, v86, v87
	v_mfma_f32_32x32x16_bf16 v[0:15], v[166:169], v[220:223], v[0:15]
	ds_read_b64_tr_b16 v[220:221], v191 offset:0x1200
	ds_read_b64_tr_b16 v[222:223], v191 offset:0x1a00
	v_max3_f32 v232, v232, v88, v89
	v_max3_f32 v232, v232, v90, v91
	v_max3_f32 v232, v232, v92, v93
	v_max3_f32 v232, v232, v94, v95
	v_max3_f32 v232, v232, v64, v65
	v_max3_f32 v232, v232, v66, v67
	v_mfma_f32_32x32x16_bf16 v[0:15], v[170:173], v[224:227], v[0:15]
	ds_read_b64_tr_b16 v[224:225], v191 offset:0x2200
	ds_read_b64_tr_b16 v[226:227], v191 offset:0x2a00
	v_max3_f32 v232, v232, v68, v69
	v_max3_f32 v232, v232, v70, v71
	v_max3_f32 v232, v232, v72, v73
	v_max3_f32 v232, v232, v74, v75
	v_max3_f32 v232, v232, v76, v77
	v_max3_f32 v232, v232, v78, v79
	v_mfma_f32_32x32x16_bf16 v[0:15], v[174:177], v[242:245], v[0:15]
	ds_read_b64_tr_b16 v[242:243], v191 offset:0x3200
	ds_read_b64_tr_b16 v[244:245], v191 offset:0x3a00
	v_mov_b32_e32 v233, v232
	s_nop 1
	v_permlane32_swap_b32_e32 v232, v233
	v_max_f32_e32 v233, v233, v233
	v_max_f32_e32 v232, v232, v232
	v_max_f32_e32 v232, v232, v233
	s_waitcnt lgkmcnt(0)
	v_mfma_f32_32x32x16_bf16 v[48:63], v[162:165], v[216:219], v[48:63]
	ds_read_b64_tr_b16 v[216:217], v191 offset:0x400
	ds_read_b64_tr_b16 v[218:219], v191 offset:0xc00
	v_sub_f32_e32 v233, v232, v210
	v_cmp_ge_f32_e32 vcc, s68, v233
	v_max_f32_e32 v233, v210, v210
	v_max_f32_e32 v232, v233, v232
	v_sub_f32_e32 v233, v210, v232
	v_mul_f32_e32 v233, 0x3e0293ee, v233
	v_mfma_f32_32x32x16_bf16 v[48:63], v[166:169], v[220:223], v[48:63]
	ds_read_b64_tr_b16 v[220:221], v191 offset:0x1400
	ds_read_b64_tr_b16 v[222:223], v191 offset:0x1c00
	s_cmp_eq_u64 vcc, exec
	s_cselect_b64 s[8:9], -1, 0
	v_exp_f32_e32 v233, v233
	v_mfma_f32_32x32x16_bf16 v[48:63], v[170:173], v[224:227], v[48:63]
	ds_read_b64_tr_b16 v[224:225], v191 offset:0x2400
	ds_read_b64_tr_b16 v[226:227], v191 offset:0x2c00
	v_cndmask_b32_e64 v210, v232, v210, s[8:9]
	v_mul_f32_e32 v250, 0xbe0293ee, v210
	v_fmamk_f32 v80, v80, 0x3e0293ee, v250
	v_fmamk_f32 v81, v81, 0x3e0293ee, v250
	v_fmamk_f32 v82, v82, 0x3e0293ee, v250
	v_fmamk_f32 v83, v83, 0x3e0293ee, v250
	v_mfma_f32_32x32x16_bf16 v[48:63], v[174:177], v[242:245], v[48:63]
	ds_read_b64_tr_b16 v[242:243], v191 offset:0x3400
	ds_read_b64_tr_b16 v[244:245], v191 offset:0x3c00
	v_fmamk_f32 v84, v84, 0x3e0293ee, v250
	v_fmamk_f32 v85, v85, 0x3e0293ee, v250
	v_fmamk_f32 v86, v86, 0x3e0293ee, v250
	v_fmamk_f32 v87, v87, 0x3e0293ee, v250
	v_fmamk_f32 v88, v88, 0x3e0293ee, v250
	v_fmamk_f32 v89, v89, 0x3e0293ee, v250
	s_waitcnt lgkmcnt(0)
	v_mfma_f32_32x32x16_bf16 v[32:47], v[162:165], v[216:219], v[32:47]
	ds_read_b64_tr_b16 v[216:217], v191 offset:0x600
	ds_read_b64_tr_b16 v[218:219], v191 offset:0xe00
	v_fmamk_f32 v90, v90, 0x3e0293ee, v250
	v_fmamk_f32 v91, v91, 0x3e0293ee, v250
	v_fmamk_f32 v92, v92, 0x3e0293ee, v250
	v_fmamk_f32 v93, v93, 0x3e0293ee, v250
	v_fmamk_f32 v94, v94, 0x3e0293ee, v250
	v_fmamk_f32 v95, v95, 0x3e0293ee, v250
	v_mfma_f32_32x32x16_bf16 v[32:47], v[166:169], v[220:223], v[32:47]
	ds_read_b64_tr_b16 v[220:221], v191 offset:0x1600
	ds_read_b64_tr_b16 v[222:223], v191 offset:0x1e00
	v_exp_f32_e32 v80, v80
	v_exp_f32_e32 v81, v81
	v_exp_f32_e32 v82, v82
	v_mfma_f32_32x32x16_bf16 v[32:47], v[170:173], v[224:227], v[32:47]
	ds_read_b64_tr_b16 v[224:225], v191 offset:0x2600
	ds_read_b64_tr_b16 v[226:227], v191 offset:0x2e00
	v_exp_f32_e32 v83, v83
	v_exp_f32_e32 v84, v84
	v_exp_f32_e32 v85, v85
	v_mfma_f32_32x32x16_bf16 v[32:47], v[174:177], v[242:245], v[32:47]
	ds_read_b64_tr_b16 v[242:243], v191 offset:0x3600
	ds_read_b64_tr_b16 v[244:245], v191 offset:0x3e00
	v_exp_f32_e32 v86, v86
	v_exp_f32_e32 v87, v87
	v_exp_f32_e32 v88, v88
	s_waitcnt lgkmcnt(0)
	v_mfma_f32_32x32x16_bf16 v[16:31], v[162:165], v[216:219], v[16:31]
	v_exp_f32_e32 v89, v89
	v_exp_f32_e32 v90, v90
	v_exp_f32_e32 v91, v91
	v_mfma_f32_32x32x16_bf16 v[16:31], v[166:169], v[220:223], v[16:31]
	v_exp_f32_e32 v92, v92
	v_exp_f32_e32 v93, v93
	v_mfma_f32_32x32x16_bf16 v[16:31], v[170:173], v[224:227], v[16:31]
	v_exp_f32_e32 v94, v94
	v_exp_f32_e32 v95, v95
	v_mfma_f32_32x32x16_bf16 v[16:31], v[174:177], v[242:245], v[16:31]
	s_barrier
; #define SBAR() __builtin_amdgcn_sched_barrier(0)
; #define SLOAD(i, k0) do { sr_[i].vs0 = St::ld8(&Vh[(long)((k0) + sr) * LDK + sc]); sr_[i].vs1 = St::ld8(&Vh[(long)((k0) + 32 + sr) * LDK + sc]); \
;     sr_[i].ks0 = St::ld8(&Kh[(long)((k0) + sr) * LDK + sc]); sr_[i].ks1 = St::ld8(&Kh[(long)((k0) + 32 + sr) * LDK + sc]); } while (0)
; #define SWAIT() do { if constexpr (SDEPTH == 2) asm volatile("s_waitcnt vmcnt(4)" ::: "memory"); else asm volatile("s_waitcnt vmcnt(0)" ::: "memory"); } while (0)
; #define RESC(a) do { if (__any((a) < 1.f)) { if (hi == 0) al_l[r32] = (a); asm volatile("s_waitcnt lgkmcnt(0)" ::: "memory"); \
;     for (int d = 0; d < 4; ++d) for (int r = 0; r < 16; ++r) o[d][r] *= al_l[crow(r, hi)]; } } while (0)
; __device__ __forceinline__ void attn_dense_body(const bf16* __restrict__ Qb, const bf16* __restrict__ Kh, const bf16* __restrict__ Vh,
;                                                 const unsigned short* __restrict__ Gb, unsigned short* __restrict__ Yb, int seq, char* lds, const int tid) {
;     ...
;     __syncthreads(); SWAIT(); SWRITE(0, SE);
;     RESC(alB); __syncthreads();
;     SBAR(); qkt(pA0, pA1, K_lds, qr, r32, hi);
;     finishSM(pB0, pB1, alB, l_reg, pa0, pa1, pa2, pa3); SBAR();
;     if (SDEPTH == 1 || j + 3 < NT) SLOAD(SE, (j + 1 + SDEPTH) * KVBLK); SBAR();
;     pv_d0(o, vb0 + (int)SHM_V, pa0, pa1, pa2, pa3); partialSM(pA0, pA1, m_reg, mnA, alA);
;     __syncthreads(); SWAIT(); SWRITE(1, SO);
;     RESC(alA); __syncthreads();
	s_waitcnt vmcnt(4)
	v_cndmask_b32_e64 v213, v233, 1.0, s[8:9]
	v_cmp_gt_f32_e32 vcc, 1.0, v213
	s_waitcnt vmcnt(3)
	ds_write_b128 v204, v[146:149] offset:16384
	s_waitcnt vmcnt(2)
	ds_write_b128 v205, v[150:153] offset:16384
	s_waitcnt vmcnt(1)
	ds_write_b128 v202, v[154:157] offset:49152
	s_waitcnt vmcnt(0)
	ds_write_b128 v203, v[158:161] offset:49152
	s_cbranch_vccz .LBB0_612
	s_and_saveexec_b64 s[18:19], s[6:7]
	ds_write_b32 v189, v213 offset:128
	s_or_b64 exec, exec, s[18:19]
	s_waitcnt lgkmcnt(0)
	v_add_u32_e32 v158, v181, v180
	ds_read_b128 v[146:149], v158 offset:224
	ds_read_b128 v[150:153], v158 offset:192
	ds_read_b128 v[154:157], v158 offset:160
	ds_read_b128 v[158:161], v158 offset:128
	s_waitcnt lgkmcnt(3)
	v_pk_mul_f32 v[12:13], v[12:13], v[146:147]
	s_waitcnt lgkmcnt(2)
	v_pk_mul_f32 v[8:9], v[8:9], v[150:151]
	s_waitcnt lgkmcnt(1)
	v_pk_mul_f32 v[4:5], v[4:5], v[154:155]
	v_pk_mul_f32 v[14:15], v[14:15], v[148:149]
	v_pk_mul_f32 v[10:11], v[10:11], v[152:153]
	v_pk_mul_f32 v[6:7], v[6:7], v[156:157]
	s_waitcnt lgkmcnt(0)
	v_pk_mul_f32 v[2:3], v[2:3], v[160:161]
	v_pk_mul_f32 v[0:1], v[0:1], v[158:159]
	v_pk_mul_f32 v[60:61], v[60:61], v[146:147]
	v_pk_mul_f32 v[56:57], v[56:57], v[150:151]
	v_pk_mul_f32 v[52:53], v[52:53], v[154:155]
	v_pk_mul_f32 v[62:63], v[62:63], v[148:149]
	v_pk_mul_f32 v[58:59], v[58:59], v[152:153]
	v_pk_mul_f32 v[54:55], v[54:55], v[156:157]
	v_pk_mul_f32 v[50:51], v[50:51], v[160:161]
	v_pk_mul_f32 v[48:49], v[48:49], v[158:159]
	v_pk_mul_f32 v[44:45], v[44:45], v[146:147]
	v_pk_mul_f32 v[40:41], v[40:41], v[150:151]
	v_pk_mul_f32 v[36:37], v[36:37], v[154:155]
	v_pk_mul_f32 v[46:47], v[46:47], v[148:149]
	v_pk_mul_f32 v[42:43], v[42:43], v[152:153]
	v_pk_mul_f32 v[38:39], v[38:39], v[156:157]
	v_pk_mul_f32 v[34:35], v[34:35], v[160:161]
	v_pk_mul_f32 v[32:33], v[32:33], v[158:159]
	v_pk_mul_f32 v[28:29], v[28:29], v[146:147]
	v_pk_mul_f32 v[24:25], v[24:25], v[150:151]
	v_pk_mul_f32 v[20:21], v[20:21], v[154:155]
	v_pk_mul_f32 v[30:31], v[30:31], v[148:149]
	v_pk_mul_f32 v[26:27], v[26:27], v[152:153]
	v_pk_mul_f32 v[22:23], v[22:23], v[156:157]
	v_pk_mul_f32 v[18:19], v[18:19], v[160:161]
	v_pk_mul_f32 v[16:17], v[16:17], v[158:159]
.LBB0_612:
	v_mul_f32_e32 v146, 0xbe0293ee, v210
	v_mov_b32_e32 v223, v80
	v_mov_b32_e32 v224, v81
	v_mov_b32_e32 v225, v82
	v_mov_b32_e32 v227, v83
	v_mov_b32_e32 v229, v84
	v_mov_b32_e32 v230, v85
	v_mov_b32_e32 v226, v86
	v_mov_b32_e32 v228, v87
	v_mov_b32_e32 v215, v88
	v_mov_b32_e32 v217, v89
	v_mov_b32_e32 v219, v90
	v_mov_b32_e32 v221, v91
	v_mov_b32_e32 v216, v92
	v_mov_b32_e32 v218, v93
	v_mov_b32_e32 v220, v94
	v_mov_b32_e32 v222, v95
	v_pk_fma_f32 v[176:177], v[64:65], s[84:85], v[146:147] op_sel_hi:[1,0,0]
	v_add_f32_e32 v64, v211, v212
	v_fmac_f32_e32 v64, v209, v190
	v_add_f32_e32 v190, v231, v241
	v_pk_fma_f32 v[174:175], v[66:67], s[84:85], v[146:147] op_sel_hi:[1,0,0]
	v_pk_fma_f32 v[170:171], v[68:69], s[84:85], v[146:147] op_sel_hi:[1,0,0]
	v_pk_fma_f32 v[166:167], v[70:71], s[84:85], v[146:147] op_sel_hi:[1,0,0]
	v_pk_fma_f32 v[164:165], v[72:73], s[84:85], v[146:147] op_sel_hi:[1,0,0]
	v_pk_fma_f32 v[172:173], v[74:75], s[84:85], v[146:147] op_sel_hi:[1,0,0]
	v_pk_fma_f32 v[168:169], v[76:77], s[84:85], v[146:147] op_sel_hi:[1,0,0]
	v_pk_fma_f32 v[162:163], v[78:79], s[84:85], v[146:147] op_sel_hi:[1,0,0]
	v_fmac_f32_e32 v190, v64, v214
	s_add_i32 s40, s40, 2
	v_lshl_add_u64 v[182:183], v[182:183], 0, s[82:83]
	s_and_b64 vcc, exec, s[12:13]
	s_waitcnt lgkmcnt(0)
	s_barrier
	s_cbranch_vccnz .LBB0_614
	v_mov_b32_e32 v209, v213
	s_branch .LBB0_602
